# lnpass (old phase 14) moved into phase 6: scan workgroups 4-127 take row groups [0,1376) after their scan, attention workgroups the rest after the T GEMM; phase 14 and its grid barrier removed; FFN2 c
# speedup vs baseline: 1.0037x; 1.0003x over previous
;     __device__ __forceinline__ unsigned char* ws() const { return (unsigned char*)ptr(37); }
; #define ws (p.ws())
; __device__ __forceinline__ void sub_barrier(const Ctx& p, unsigned n) {
;     asm volatile("s_waitcnt vmcnt(0)" ::: "memory");
;     __syncthreads();
;     if (threadIdx.x == 0) {
;         unsigned* c = (unsigned*)(p.ws() + WS_CTR) + 128;
;         __builtin_amdgcn_fence(__ATOMIC_RELEASE, "agent");
;         asm volatile("s_waitcnt vmcnt(0)" ::: "memory");
;         __hip_atomic_fetch_add(c, 1u, __ATOMIC_RELAXED, __HIP_MEMORY_SCOPE_AGENT);
;         while (__hip_atomic_load(c, __ATOMIC_RELAXED, __HIP_MEMORY_SCOPE_AGENT) < n) __builtin_amdgcn_s_sleep(20);
.Lln_sa:
	s_or_b64 exec, exec, s[2:3]
.Lffn2w_done:
	s_cmpk_gt_u32 s28, 3
	s_cbranch_scc1 .Ltg_scan_skip
	s_waitcnt vmcnt(0) lgkmcnt(0)
	s_barrier
	v_cmp_eq_u32_e32 vcc, 0, v180
	s_and_saveexec_b64 s[2:3], vcc
	s_cbranch_execz .Ltg_sync_done
	v_mov_b32_e32 v0, 0x23528
	ds_read_b64 v[0:1], v0
	s_waitcnt lgkmcnt(0)
	v_readfirstlane_b32 s4, v0
	v_readfirstlane_b32 s5, v1
	s_nop 4
	s_add_u32 s4, s4, 0x3180200
	s_addc_u32 s5, s5, 0
	v_mov_b32_e32 v0, 0

;     __device__ __forceinline__ unsigned char* ws() const { return (unsigned char*)ptr(37); }
; #define ws (p.ws())
; __device__ __forceinline__ void sub_barrier(const Ctx& p, unsigned n) {
;     ...
;     if (threadIdx.x == 0) {
;         unsigned* c = (unsigned*)(p.ws() + WS_CTR) + 128;
;         __builtin_amdgcn_fence(__ATOMIC_RELEASE, "agent");
;         asm volatile("s_waitcnt vmcnt(0)" ::: "memory");
;         __hip_atomic_fetch_add(c, 1u, __ATOMIC_RELAXED, __HIP_MEMORY_SCOPE_AGENT);
;         while (__hip_atomic_load(c, __ATOMIC_RELAXED, __HIP_MEMORY_SCOPE_AGENT) < n) __builtin_amdgcn_s_sleep(20);
;         __builtin_amdgcn_fence(__ATOMIC_ACQUIRE, "agent");
;         asm volatile("s_waitcnt vmcnt(0)" ::: "memory");
.Ltg_scan_skip:
	v_cmp_eq_u32_e32 vcc, 0, v180
	s_and_saveexec_b64 s[2:3], vcc
	s_cbranch_execz .Lln_w1_x
	v_mov_b32_e32 v0, 0x23528
	ds_read_b64 v[0:1], v0
	s_waitcnt lgkmcnt(0)
	v_readfirstlane_b32 s4, v0
	v_readfirstlane_b32 s5, v1
	s_nop 4
	s_add_u32 s4, s4, 0x3180300
	s_addc_u32 s5, s5, 0
	v_mov_b32_e32 v0, 0
.Lln_w1_s0:
	global_load_dword v1, v0, s[4:5] offset:0 sc1
	s_waitcnt vmcnt(0)
	v_cmp_gt_u32_e32 vcc, 0x80, v1
	s_cbranch_vccz .Lln_w1_s0_ok
	s_sleep 4
	s_branch .Lln_w1_s0
.Lln_w1_s0_ok:
.Lln_w1_s1:
	global_load_dword v1, v0, s[4:5] offset:32 sc1
	s_waitcnt vmcnt(0)
	v_cmp_gt_u32_e32 vcc, 0x80, v1
	s_cbranch_vccz .Lln_w1_s1_ok
	s_sleep 4
	s_branch .Lln_w1_s1

;     __device__ __forceinline__ const float* in(int i) const { return (const float*)ptr(i); }
;     __device__ __forceinline__ unsigned char* ws() const { return (unsigned char*)ptr(37); }
; #define ws (p.ws())
; __device__ __forceinline__ void phase_lnpass(const Ctx& p) {
;     const int tid = threadIdx.x, c8 = tid & 7, h = (tid >> 3) & 7, rr = tid >> 6, c = h * 64 + 8 * c8;
;     const bf16_t* ZRW = (const bf16_t*)(p.ws() + WS_ZRW); const bf16_t* AB = (const bf16_t*)(p.ws() + WS_ABUF); const bf16_t* GG = (const bf16_t*)(p.ws() + WS_GG);
;     bf16_t* ORW = (bf16_t*)(p.ws() + WS_ORW);
;     float mur[8], muk[8], muv[8], kac[8], rkc[8], lg[8], lb[8];
; #pragma unroll
;     for (int e = 0; e < 8; ++e) { mur[e] = p.in(17)[c + e]; muk[e] = p.in(17)[512 + c + e]; muv[e] = p.in(17)[1024 + c + e]; kac[e] = p.in(24)[c + e]; rkc[e] = p.in(25)[c + e]; lg[e] = p.in(26)[c + e]; lb[e] = p.in(27)[c + e]; }
;     struct LR { u32x4 zr, zrp, zk, zkp, zv, zvp, ab, gg, yy; };
;     auto ldrow = [&](LR& L, int row) {
;         const int rp = row > 0 ? row - 1 : 0;
;         L.zr = *(const u32x4*)(ZRW + (size_t)row * SHW + c); L.zrp = *(const u32x4*)(ZRW + (size_t)rp * SHW + c);
;         L.zk = *(const u32x4*)(ZRW + (size_t)row * SHW + 512 + c); L.zkp = *(const u32x4*)(ZRW + (size_t)rp * SHW + 512 + c);
;         L.zv = *(const u32x4*)(ZRW + (size_t)row * SHW + 1024 + c); L.zvp = *(const u32x4*)(ZRW + (size_t)rp * SHW + 1024 + c);
;         L.ab = *(const u32x4*)(AB + (size_t)row * 512 + c); L.gg = *(const u32x4*)(GG + (size_t)row * 512 + c); L.yy = *(const u32x4*)(ORW + (size_t)row * 512 + c);
;     };
;     LR La, Lb;
;     if ((int)blockIdx.x < MR / 8) ldrow(La, blockIdx.x * 8 + rr);
;     for (int it = blockIdx.x; it < MR / 8; it += gridDim.x) {
;         const int row = it * 8 + rr;
;         const bool more = it + (int)gridDim.x < MR / 8;
;         if (more) ldrow(Lb, (it + gridDim.x) * 8 + rr);
.Lln_w1_x:
	s_or_b64 exec, exec, s[2:3]
	s_waitcnt lgkmcnt(0)
	s_barrier
	s_sub_u32 s70, s28, 4
	s_movk_i32 s72, 0x7c
	s_add_i32 s2, 0, 0x23528
	s_waitcnt vmcnt(0)
	v_mov_b32_e32 v0, s2
	ds_read_b64 v[0:1], v0
	s_add_i32 s2, 0, 0x23488
	v_mov_b32_e32 v2, s2
	s_add_i32 s6, 0, 0x234c0
	ds_read_b64 v[8:9], v2
	s_waitcnt lgkmcnt(0)
	v_readfirstlane_b32 s2, v0
	v_mov_b32_e32 v0, s6
	s_add_i32 s6, 0, 0x234d0
	v_mov_b32_e32 v4, s6
	v_readfirstlane_b32 s3, v1
	ds_read_b128 v[0:3], v0
	ds_read_b128 v[4:7], v4
	v_readfirstlane_b32 s12, v8
	v_readfirstlane_b32 s13, v9
	s_cmpk_gt_i32 s70, 0x55f
	s_waitcnt lgkmcnt(1)
	v_readfirstlane_b32 s14, v0
	v_readfirstlane_b32 s15, v1
	v_readfirstlane_b32 s16, v2
	v_readfirstlane_b32 s17, v3
	s_waitcnt lgkmcnt(0)
	v_readfirstlane_b32 s10, v4
	v_readfirstlane_b32 s11, v5
	v_readfirstlane_b32 s8, v6
	v_readfirstlane_b32 s9, v7
	s_cbranch_scc1 .Lln1_done
	v_lshlrev_b32_e32 v0, 3, v180
	v_and_b32_e32 v56, 0x1f8, v0
	v_mov_b32_e32 v141, 0
	v_lshlrev_b32_e32 v140, 2, v56
	v_lshl_add_u64 v[32:33], s[12:13], 0, v[140:141]
	global_load_dwordx4 v[0:3], v140, s[12:13] offset:16
	global_load_dwordx4 v[4:7], v140, s[12:13]
	global_load_dwordx4 v[8:11], v140, s[12:13] offset:2064
	global_load_dwordx4 v[12:15], v140, s[12:13] offset:2048
	global_load_dwordx4 v[16:19], v140, s[14:15] offset:16
	global_load_dwordx4 v[20:23], v140, s[14:15]
	global_load_dwordx4 v[24:27], v140, s[16:17] offset:16
	global_load_dwordx4 v[28:31], v140, s[16:17]
	s_movk_i32 s12, 0x1000
	v_add_co_u32_e32 v60, vcc, s12, v32
	s_mov_b64 s[6:7], 0x1000
	s_nop 0
	v_addc_co_u32_e32 v61, vcc, 0, v33, vcc
	v_lshl_add_u64 v[58:59], v[32:33], 0, s[6:7]
	global_load_dwordx4 v[32:35], v[60:61], off
	global_load_dwordx4 v[36:39], v[58:59], off offset:16
	global_load_dwordx4 v[40:43], v140, s[10:11] offset:16
	global_load_dwordx4 v[44:47], v140, s[10:11]
	global_load_dwordx4 v[48:51], v140, s[8:9] offset:16
	global_load_dwordx4 v[52:55], v140, s[8:9]
	s_add_u32 s8, s2, 0x8340000
	s_addc_u32 s9, s3, 0
	s_add_u32 s10, s2, 0x4240000
	s_addc_u32 s11, s3, 0
	s_add_u32 s14, s2, 0x3200000
	v_lshrrev_b32_e32 v152, 6, v180
	s_addc_u32 s15, s3, 0
	s_lshl_b32 s12, s70, 3
	v_add_u32_e32 v58, s12, v152
	v_max_i32_e32 v57, 1, v58
	s_movk_i32 s13, 0xe00
	v_mov_b64_e32 v[60:61], s[8:9]
	v_add_u32_e32 v57, -1, v57
	v_mad_i64_i32 v[62:63], s[16:17], v58, s13, v[60:61]
	v_lshlrev_b32_e32 v140, 1, v56
	v_lshl_add_u64 v[62:63], v[62:63], 0, v[140:141]
	v_mad_u64_u32 v[60:61], s[16:17], v57, s13, v[60:61]
	v_ashrrev_i32_e32 v59, 31, v58
	v_lshl_add_u64 v[60:61], v[60:61], 0, v[140:141]
	global_load_dwordx4 v[104:107], v[62:63], off
	global_load_dwordx4 v[108:111], v[62:63], off offset:1024
	global_load_dwordx4 v[124:127], v[60:61], off
	global_load_dwordx4 v[92:95], v[62:63], off offset:2048
	global_load_dwordx4 v[116:119], v[60:61], off offset:1024
	global_load_dwordx4 v[120:123], v[60:61], off offset:2048
	v_lshlrev_b64 v[58:59], 10, v[58:59]
	v_lshl_add_u64 v[60:61], s[14:15], 0, v[58:59]
	v_lshl_add_u64 v[62:63], s[10:11], 0, v[58:59]
	v_lshl_add_u64 v[58:59], s[2:3], 0, v[58:59]
	v_lshl_add_u64 v[60:61], v[60:61], 0, v[140:141]
	v_lshl_add_u64 v[58:59], v[58:59], 0, v[140:141]
	v_lshl_add_u64 v[62:63], v[62:63], 0, v[140:141]
	global_load_dwordx4 v[112:115], v[60:61], off
	global_load_dwordx4 v[100:103], v[62:63], off
	global_load_dwordx4 v[96:99], v[58:59], off
	v_lshl_add_u64 v[146:147], s[2:3], 0, v[140:141]
	s_add_i32 s2, s70, s72
	v_lshl_add_u64 v[142:143], s[14:15], 0, v[140:141]
	v_lshl_add_u64 v[144:145], s[10:11], 0, v[140:141]
	v_lshl_add_u64 v[148:149], s[8:9], 0, v[140:141]
	s_lshl_b32 s14, s2, 3
	s_lshl_b32 s15, s72, 3
	s_movk_i32 s16, 0x4000
	s_movk_i32 s17, 0x3fff
	s_add_i32 s18, 0, 0x23428
	s_movk_i32 s19, 0x1c00
	v_lshlrev_b32_e32 v140, 2, v56
	v_mov_b32_e32 v153, 0x3a27c5ac
	s_mov_b32 s20, 0xf800000
	v_mov_b32_e32 v154, 0x260
	v_mov_b32_e32 v155, 0xfff
	s_mov_b32 s21, s70
	s_branch .Lln1_c

; __device__ __forceinline__ void phase_lnpass(const Ctx& p) {
;     ...
;     auto ldrow = [&](LR& L, int row) {
;         const int rp = row > 0 ? row - 1 : 0;
;         L.zr = *(const u32x4*)(ZRW + (size_t)row * SHW + c); L.zrp = *(const u32x4*)(ZRW + (size_t)rp * SHW + c);
;         L.zk = *(const u32x4*)(ZRW + (size_t)row * SHW + 512 + c); L.zkp = *(const u32x4*)(ZRW + (size_t)rp * SHW + 512 + c);
;         L.zv = *(const u32x4*)(ZRW + (size_t)row * SHW + 1024 + c); L.zvp = *(const u32x4*)(ZRW + (size_t)rp * SHW + 1024 + c);
;         L.ab = *(const u32x4*)(AB + (size_t)row * 512 + c); L.gg = *(const u32x4*)(GG + (size_t)row * 512 + c); L.yy = *(const u32x4*)(ORW + (size_t)row * 512 + c);
;     };
;     LR La, Lb;
;     if ((int)blockIdx.x < MR / 8) ldrow(La, blockIdx.x * 8 + rr);
;     for (int it = blockIdx.x; it < MR / 8; it += gridDim.x) {
;         const int row = it * 8 + rr;
;         const bool more = it + (int)gridDim.x < MR / 8;
;         if (more) ldrow(Lb, (it + gridDim.x) * 8 + rr);
.Lln1_c:
	s_add_i32 s21, s21, s72
	s_cmpk_gt_i32 s21, 0x55f
	s_cselect_b64 s[8:9], -1, 0
	s_and_b64 vcc, exec, s[8:9]
	s_cbranch_vccnz .Lln1_d
	v_add_u32_e32 v80, s14, v152
	v_max_i32_e32 v56, 1, v80
	v_add_u32_e32 v56, -1, v56
	v_mad_i64_i32 v[68:69], s[2:3], v80, s13, v[148:149]
	v_mad_u64_u32 v[76:77], s[2:3], v56, s13, v[148:149]
	global_load_dwordx4 v[56:59], v[68:69], off
	global_load_dwordx4 v[64:67], v[68:69], off offset:1024
	global_load_dwordx4 v[60:63], v[76:77], off
	global_load_dwordx4 v[72:75], v[68:69], off offset:2048
	s_nop 0
	global_load_dwordx4 v[68:71], v[76:77], off offset:1024
	s_nop 0
	global_load_dwordx4 v[76:79], v[76:77], off offset:2048
	v_ashrrev_i32_e32 v81, 31, v80
	v_lshlrev_b64 v[88:89], 10, v[80:81]
	v_lshl_add_u64 v[80:81], v[142:143], 0, v[88:89]
	v_lshl_add_u64 v[84:85], v[144:145], 0, v[88:89]
	v_lshl_add_u64 v[88:89], v[146:147], 0, v[88:89]
	global_load_dwordx4 v[80:83], v[80:81], off
	s_nop 0
	global_load_dwordx4 v[84:87], v[84:85], off
	s_nop 0
	global_load_dwordx4 v[88:91], v[88:89], off

;     __device__ __forceinline__ unsigned char* ws() const { return (unsigned char*)ptr(37); }
; #define ws (p.ws())
; __device__ __forceinline__ void sub_barrier(const Ctx& p, unsigned n) {
;     asm volatile("s_waitcnt vmcnt(0)" ::: "memory");
;     __syncthreads();
;     if (threadIdx.x == 0) {
;         unsigned* c = (unsigned*)(p.ws() + WS_CTR) + 128;
; __global__ void __launch_bounds__(512) fwd_kernel(Params prm) {
;     ...
;         if (blockIdx.x >= 128) {
;             sub_barrier(p, 128u);
;             EpiGate1 E{(bf16_t*)(ws + WS_KB), (const bf16_t*)(ws + WS_GATE)};
;             pg8::Gemm g{(const bf16_t*)(ws + WS_QB), (const bf16_t*)(ws + WS_WAT), MP, DM, 512, 512}; pg8::StaticOrder S; S.init(MP, DM, 128, (int)blockIdx.x - 128);
;             pg8::gemm_phase<EpiGate1, pg8::StaticOrder, true, true>(lds, g, S, E);
.LBB0_1868:
	s_waitcnt vmcnt(0)
	s_barrier
	s_cmpk_lt_u32 s28, 0x80
	s_cbranch_scc1 .Lln2_skip
	v_cmp_eq_u32_e32 vcc, 0, v180
	s_and_saveexec_b64 s[2:3], vcc
	s_cbranch_execz .Lln_w2_x
	v_mov_b32_e32 v0, 0x23528
	ds_read_b64 v[0:1], v0
	s_waitcnt lgkmcnt(0)
	v_readfirstlane_b32 s4, v0
	v_readfirstlane_b32 s5, v1
	s_nop 4
	s_add_u32 s4, s4, 0x3180300
	s_addc_u32 s5, s5, 0
	v_mov_b32_e32 v0, 0

;     __device__ __forceinline__ const float* in(int i) const { return (const float*)ptr(i); }
;     __device__ __forceinline__ unsigned char* ws() const { return (unsigned char*)ptr(37); }
; #define ws (p.ws())
; __device__ __forceinline__ void phase_lnpass(const Ctx& p) {
;     const int tid = threadIdx.x, c8 = tid & 7, h = (tid >> 3) & 7, rr = tid >> 6, c = h * 64 + 8 * c8;
;     const bf16_t* ZRW = (const bf16_t*)(p.ws() + WS_ZRW); const bf16_t* AB = (const bf16_t*)(p.ws() + WS_ABUF); const bf16_t* GG = (const bf16_t*)(p.ws() + WS_GG);
;     bf16_t* ORW = (bf16_t*)(p.ws() + WS_ORW);
;     float mur[8], muk[8], muv[8], kac[8], rkc[8], lg[8], lb[8];
; #pragma unroll
;     for (int e = 0; e < 8; ++e) { mur[e] = p.in(17)[c + e]; muk[e] = p.in(17)[512 + c + e]; muv[e] = p.in(17)[1024 + c + e]; kac[e] = p.in(24)[c + e]; rkc[e] = p.in(25)[c + e]; lg[e] = p.in(26)[c + e]; lb[e] = p.in(27)[c + e]; }
;     struct LR { u32x4 zr, zrp, zk, zkp, zv, zvp, ab, gg, yy; };
;     auto ldrow = [&](LR& L, int row) {
;         const int rp = row > 0 ? row - 1 : 0;
;         L.zr = *(const u32x4*)(ZRW + (size_t)row * SHW + c); L.zrp = *(const u32x4*)(ZRW + (size_t)rp * SHW + c);
;         L.zk = *(const u32x4*)(ZRW + (size_t)row * SHW + 512 + c); L.zkp = *(const u32x4*)(ZRW + (size_t)rp * SHW + 512 + c);
;         L.zv = *(const u32x4*)(ZRW + (size_t)row * SHW + 1024 + c); L.zvp = *(const u32x4*)(ZRW + (size_t)rp * SHW + 1024 + c);
;         L.ab = *(const u32x4*)(AB + (size_t)row * 512 + c); L.gg = *(const u32x4*)(GG + (size_t)row * 512 + c); L.yy = *(const u32x4*)(ORW + (size_t)row * 512 + c);
;     };
;     LR La, Lb;
;     if ((int)blockIdx.x < MR / 8) ldrow(La, blockIdx.x * 8 + rr);
;     for (int it = blockIdx.x; it < MR / 8; it += gridDim.x) {
;         const int row = it * 8 + rr;
;         const bool more = it + (int)gridDim.x < MR / 8;
;         if (more) ldrow(Lb, (it + gridDim.x) * 8 + rr);
.Lln_w2_x:
	s_or_b64 exec, exec, s[2:3]
	s_waitcnt lgkmcnt(0)
	s_barrier
	s_movk_i32 s72, 0x80
	s_add_i32 s71, s28, 0x4e0
	s_add_i32 s2, 0, 0x23528
	s_waitcnt vmcnt(0)
	v_mov_b32_e32 v0, s2
	ds_read_b64 v[0:1], v0
	s_add_i32 s2, 0, 0x23488
	v_mov_b32_e32 v2, s2
	s_add_i32 s6, 0, 0x234c0
	ds_read_b64 v[8:9], v2
	s_waitcnt lgkmcnt(0)
	v_readfirstlane_b32 s2, v0
	v_mov_b32_e32 v0, s6
	s_add_i32 s6, 0, 0x234d0
	v_mov_b32_e32 v4, s6
	v_readfirstlane_b32 s3, v1
	ds_read_b128 v[0:3], v0
	ds_read_b128 v[4:7], v4
	v_readfirstlane_b32 s12, v8
	v_readfirstlane_b32 s13, v9
	s_cmpk_gt_i32 s71, 0x80f
	s_waitcnt lgkmcnt(1)
	v_readfirstlane_b32 s14, v0
	v_readfirstlane_b32 s15, v1
	v_readfirstlane_b32 s16, v2
	v_readfirstlane_b32 s17, v3
	s_waitcnt lgkmcnt(0)
	v_readfirstlane_b32 s10, v4
	v_readfirstlane_b32 s11, v5
	v_readfirstlane_b32 s8, v6
	v_readfirstlane_b32 s9, v7
	s_cbranch_scc1 .Lln2_done
	v_lshlrev_b32_e32 v0, 3, v180
	v_and_b32_e32 v56, 0x1f8, v0
	v_mov_b32_e32 v141, 0
	v_lshlrev_b32_e32 v140, 2, v56
	v_lshl_add_u64 v[32:33], s[12:13], 0, v[140:141]
	global_load_dwordx4 v[0:3], v140, s[12:13] offset:16
	global_load_dwordx4 v[4:7], v140, s[12:13]
	global_load_dwordx4 v[8:11], v140, s[12:13] offset:2064
	global_load_dwordx4 v[12:15], v140, s[12:13] offset:2048
	global_load_dwordx4 v[16:19], v140, s[14:15] offset:16
	global_load_dwordx4 v[20:23], v140, s[14:15]
	global_load_dwordx4 v[24:27], v140, s[16:17] offset:16
	global_load_dwordx4 v[28:31], v140, s[16:17]
	s_movk_i32 s12, 0x1000
	v_add_co_u32_e32 v60, vcc, s12, v32
	s_mov_b64 s[6:7], 0x1000
	s_nop 0
	v_addc_co_u32_e32 v61, vcc, 0, v33, vcc
	v_lshl_add_u64 v[58:59], v[32:33], 0, s[6:7]
	global_load_dwordx4 v[32:35], v[60:61], off
	global_load_dwordx4 v[36:39], v[58:59], off offset:16
	global_load_dwordx4 v[40:43], v140, s[10:11] offset:16
	global_load_dwordx4 v[44:47], v140, s[10:11]
	global_load_dwordx4 v[48:51], v140, s[8:9] offset:16
	global_load_dwordx4 v[52:55], v140, s[8:9]
	s_add_u32 s8, s2, 0x8340000
	s_addc_u32 s9, s3, 0
	s_add_u32 s10, s2, 0x4240000
	s_addc_u32 s11, s3, 0
	s_add_u32 s14, s2, 0x3200000
	v_lshrrev_b32_e32 v152, 6, v180
	s_addc_u32 s15, s3, 0
	s_lshl_b32 s12, s71, 3
	v_add_u32_e32 v58, s12, v152
	v_max_i32_e32 v57, 1, v58
	s_movk_i32 s13, 0xe00
	v_mov_b64_e32 v[60:61], s[8:9]
	v_add_u32_e32 v57, -1, v57
	v_mad_i64_i32 v[62:63], s[16:17], v58, s13, v[60:61]
	v_lshlrev_b32_e32 v140, 1, v56
	v_lshl_add_u64 v[62:63], v[62:63], 0, v[140:141]
	v_mad_u64_u32 v[60:61], s[16:17], v57, s13, v[60:61]
	v_ashrrev_i32_e32 v59, 31, v58
	v_lshl_add_u64 v[60:61], v[60:61], 0, v[140:141]
	global_load_dwordx4 v[104:107], v[62:63], off
	global_load_dwordx4 v[108:111], v[62:63], off offset:1024
	global_load_dwordx4 v[124:127], v[60:61], off
	global_load_dwordx4 v[92:95], v[62:63], off offset:2048
	global_load_dwordx4 v[116:119], v[60:61], off offset:1024
	global_load_dwordx4 v[120:123], v[60:61], off offset:2048
	v_lshlrev_b64 v[58:59], 10, v[58:59]
	v_lshl_add_u64 v[60:61], s[14:15], 0, v[58:59]
	v_lshl_add_u64 v[62:63], s[10:11], 0, v[58:59]
	v_lshl_add_u64 v[58:59], s[2:3], 0, v[58:59]
	v_lshl_add_u64 v[60:61], v[60:61], 0, v[140:141]
	v_lshl_add_u64 v[58:59], v[58:59], 0, v[140:141]
	v_lshl_add_u64 v[62:63], v[62:63], 0, v[140:141]
	global_load_dwordx4 v[112:115], v[60:61], off
	global_load_dwordx4 v[100:103], v[62:63], off
	global_load_dwordx4 v[96:99], v[58:59], off
	v_lshl_add_u64 v[146:147], s[2:3], 0, v[140:141]
	s_add_i32 s2, s71, s72
	v_lshl_add_u64 v[142:143], s[14:15], 0, v[140:141]
	v_lshl_add_u64 v[144:145], s[10:11], 0, v[140:141]
	v_lshl_add_u64 v[148:149], s[8:9], 0, v[140:141]
	s_lshl_b32 s14, s2, 3
	s_lshl_b32 s15, s72, 3
	s_movk_i32 s16, 0x4000
	s_movk_i32 s17, 0x3fff
	s_add_i32 s18, 0, 0x23428
	s_movk_i32 s19, 0x1c00
	v_lshlrev_b32_e32 v140, 2, v56
	v_mov_b32_e32 v153, 0x3a27c5ac
	s_mov_b32 s20, 0xf800000
	v_mov_b32_e32 v154, 0x260
	v_mov_b32_e32 v155, 0xfff
	s_mov_b32 s21, s71
	s_branch .Lln2_c

; __device__ __forceinline__ unsigned xb_ld(unsigned* p)              { return __hip_atomic_load(p, __ATOMIC_RELAXED, __HIP_MEMORY_SCOPE_AGENT); }
; __device__ __forceinline__ void xcd_barrier_complete(unsigned* bar, unsigned x, unsigned& nloc, unsigned& nx) {
;     const unsigned G = gridDim.x * gridDim.y * gridDim.z;
;     unsigned sum, cnt, mine, sp = 0u;
;     for (;;) {
;         sum = 0u; cnt = 0u; mine = 0u;
; #pragma unroll
;         for (unsigned j = 0; j < 16; ++j) { const unsigned c = xb_ld(&bar[XB_XCNT(j)]); sum += c; cnt += (c > 0u) ? 1u : 0u; mine = (j == x) ? c : mine; }
; __device__ __forceinline__ void xcd_barrier(const XcdBarrier& b) {
;     asm volatile("s_waitcnt vmcnt(0)" ::: "memory");
;     __syncthreads();
;     if (threadIdx.x == 0) {
;         unsigned* bar = b.bar;
;         __builtin_amdgcn_s_waitcnt(0);
;         unsigned nloc = b.st[0], nx = b.st[1];
;         if (nloc == 0u) { xcd_barrier_complete(bar, b.x, nloc, nx); b.st[0] = nloc; b.st[1] = nx; }
.Lln2_done:
.Lln2_skip:
.LBB0_1869:
	s_cmp_gt_u32 s37, 7
	s_cselect_b64 s[2:3], -1, 0
	s_and_b64 s[2:3], s[40:41], s[2:3]
	s_andn2_b64 vcc, exec, s[2:3]
	s_cbranch_vccnz .LBB0_1941
	s_waitcnt vmcnt(0)
	v_readlane_b32 s0, v238, 0
	v_readlane_b32 s1, v238, 1
	s_waitcnt vmcnt(0) lgkmcnt(0)
	s_barrier
	s_and_saveexec_b64 s[2:3], s[0:1]
	s_cbranch_execz .LBB0_1940
	s_add_i32 s4, 0, 0x23800
	v_mov_b32_e32 v0, s4
	s_waitcnt vmcnt(0) expcnt(0) lgkmcnt(0)
	ds_read_b32 v2, v0
	s_add_i32 s4, 0, 0x23804
	v_mov_b32_e32 v0, s4
	ds_read_b32 v0, v0
	s_waitcnt lgkmcnt(1)
	v_cmp_ne_u32_e32 vcc, 0, v2
	s_cbranch_vccnz .LBB0_1886
	s_add_u32 s4, s30, 0x3181200
	s_addc_u32 s5, s31, 0
	s_add_u32 s6, s30, 0x3181400
	s_addc_u32 s7, s31, 0
	s_add_u32 s8, s30, 0x3181500
	s_addc_u32 s9, s31, 0
	s_add_u32 s10, s30, 0x3181600
	s_addc_u32 s11, s31, 0
	s_add_u32 s12, s30, 0x3181700
	s_addc_u32 s13, s31, 0
	s_add_u32 s14, s30, 0x3181800
	s_addc_u32 s15, s31, 0
	s_add_u32 s16, s30, 0x3181900
	s_addc_u32 s17, s31, 0
	s_add_u32 s18, s30, 0x3181a00
	s_addc_u32 s19, s31, 0
	s_add_u32 s20, s30, 0x3181b00
	s_addc_u32 s21, s31, 0
	s_add_u32 s22, s30, 0x3181c00
	s_addc_u32 s23, s31, 0
	s_add_u32 s24, s30, 0x3181d00
	s_addc_u32 s25, s31, 0
	s_add_u32 s26, s30, 0x3181e00
	s_addc_u32 s27, s31, 0
	s_add_u32 s40, s30, 0x3181f00
	s_addc_u32 s41, s31, 0
	s_add_u32 s42, s30, 0x3182000
	s_addc_u32 s43, s31, 0
	s_add_u32 s44, s30, 0x3182100
	s_addc_u32 s45, s31, 0
	s_add_u32 s46, s30, 0x3182200
	s_addc_u32 s47, s31, 0
	s_mul_i32 s33, s39, s73
	s_add_u32 s48, s30, 0x3182300
	s_mul_i32 s33, s33, s38
	s_addc_u32 s49, s31, 0
	s_mov_b32 s34, 1
	v_mov_b32_e32 v16, 0
	s_branch .LBB0_1874
